# grid barrier: non-leader workgroups poll the grid-wide TOPGEN word directly, XCD leaders no longer relay through XGEN
# speedup vs baseline: 1.0053x; 1.0048x over previous
; __device__ __forceinline__ unsigned xb_ld(unsigned* p)              { asm volatile("" : "+v"(p)); return __hip_atomic_load(p, __ATOMIC_RELAXED, __HIP_MEMORY_SCOPE_AGENT); }
; __device__ __forceinline__ unsigned xb_add(unsigned* p, unsigned v) { asm volatile("" : "+v"(p)); return __hip_atomic_fetch_add(p, v, __ATOMIC_RELAXED, __HIP_MEMORY_SCOPE_AGENT); }
; #define XB_SPIN(cond, bar) do { unsigned _sp = 0; while (cond) { __builtin_amdgcn_s_sleep(1); \
;     if ((++_sp & 255u) == 0u) { if (xb_ld(&(bar)[XB_TMO])) break; if (_sp > XB_SPIN_CAP) { (void)xb_add(&(bar)[XB_TMO], 1u); break; } } } } while (0)
; __device__ __forceinline__ void xcd_barrier(const XcdBarrier& b, int tid) {
;     ...
;         const unsigned old = xb_add(&bar[XB_XSUB(b.x)], 1u);
;         const unsigned gen = old / nloc;
;         if (old + 1u == (gen + 1u) * nloc) {
;             __builtin_amdgcn_fence(__ATOMIC_RELEASE, "agent");
;             asm volatile("s_waitcnt vmcnt(0)" ::: "memory");
;             const unsigned og = xb_add(&bar[XB_TOP], 1u);
;             const unsigned tg = og / nx;
;             if (og + 1u == (tg + 1u) * nx) xb_add(&bar[XB_TOPGEN], 1u);
;             else XB_SPIN(xb_ld(&bar[XB_TOPGEN]) == tg, bar);
;             __builtin_amdgcn_fence(__ATOMIC_ACQUIRE, "agent");
;             xb_add(&bar[XB_XGEN(b.x)], 1u);
;             asm volatile("s_waitcnt vmcnt(0)" ::: "memory");
;         } else {
;             XB_SPIN(xb_ld(&bar[XB_XGEN(b.x)]) == gen, bar);
.LBB0_113:
	s_lshl_b32 s4, s41, 8
	s_add_u32 s28, s33, s4
	s_addc_u32 s29, s40, 0
	s_add_u32 s4, s28, 0x1400
	s_addc_u32 s5, s29, 0
	v_mov_b64_e32 v[4:5], s[4:5]
	v_mov_b32_e32 v1, 1
	flat_atomic_add v1, v[4:5], v1 sc0
	v_cvt_f32_u32_e32 v3, v2
	v_sub_u32_e32 v4, 0, v2
	v_rcp_iflag_f32_e32 v3, v3
	s_nop 0
	v_mul_f32_e32 v3, 0x4f7ffffe, v3
	v_cvt_u32_f32_e32 v3, v3
	v_mul_lo_u32 v4, v4, v3
	v_mul_hi_u32 v4, v3, v4
	v_add_u32_e32 v3, v3, v4
	s_waitcnt vmcnt(0) lgkmcnt(0)
	v_mul_hi_u32 v3, v1, v3
	v_mul_lo_u32 v4, v3, v2
	v_add_u32_e32 v6, 1, v1
	v_sub_u32_e32 v1, v1, v4
	v_add_u32_e32 v5, 1, v3
	v_cmp_ge_u32_e32 vcc, v1, v2
	v_sub_u32_e32 v4, v1, v2
	s_nop 0
	v_cndmask_b32_e32 v3, v3, v5, vcc
	v_cndmask_b32_e32 v1, v1, v4, vcc
	v_add_u32_e32 v4, 1, v3
	v_cmp_ge_u32_e32 vcc, v1, v2
	s_nop 1
	v_cndmask_b32_e32 v3, v3, v4, vcc
	v_mad_u64_u32 v[4:5], s[4:5], v2, v3, v[2:3]
	v_cmp_ne_u32_e32 vcc, v6, v4
	s_and_saveexec_b64 s[4:5], vcc
	s_xor_b64 s[4:5], exec, s[4:5]
	s_cbranch_execz .LBB0_127
	s_add_u32 s6, s33, 0x200
	s_addc_u32 s7, s40, 0
	s_add_u32 s10, s33, 0x3500
	s_addc_u32 s11, s40, 0
	s_mov_b32 s26, 1
	s_mov_b64 s[8:9], 0
	v_mov_b64_e32 v[0:1], s[10:11]
	s_branch .LBB0_117

; __device__ __forceinline__ unsigned xb_ld(unsigned* p)              { asm volatile("" : "+v"(p)); return __hip_atomic_load(p, __ATOMIC_RELAXED, __HIP_MEMORY_SCOPE_AGENT); }
; __device__ __forceinline__ unsigned xb_add(unsigned* p, unsigned v) { asm volatile("" : "+v"(p)); return __hip_atomic_fetch_add(p, v, __ATOMIC_RELAXED, __HIP_MEMORY_SCOPE_AGENT); }
; #define XB_SPIN(cond, bar) do { unsigned _sp = 0; while (cond) { __builtin_amdgcn_s_sleep(1); \
;     if ((++_sp & 255u) == 0u) { if (xb_ld(&(bar)[XB_TMO])) break; if (_sp > XB_SPIN_CAP) { (void)xb_add(&(bar)[XB_TMO], 1u); break; } } } } while (0)
; __device__ __forceinline__ void xcd_barrier(const XcdBarrier& b, int tid) {
;     ...
;             const unsigned og = xb_add(&bar[XB_TOP], 1u);
;             const unsigned tg = og / nx;
;             if (og + 1u == (tg + 1u) * nx) xb_add(&bar[XB_TOPGEN], 1u);
;             else XB_SPIN(xb_ld(&bar[XB_TOPGEN]) == tg, bar);
;             __builtin_amdgcn_fence(__ATOMIC_ACQUIRE, "agent");
;             xb_add(&bar[XB_XGEN(b.x)], 1u);
.LBB0_132:
	s_or_b64 exec, exec, s[4:5]
	s_add_u32 s4, s28, 0x2400
	s_addc_u32 s5, s29, 0
	v_mov_b64_e32 v[0:1], s[4:5]
	v_mov_b32_e32 v2, 1
	s_waitcnt vmcnt(0) lgkmcnt(0)
	buffer_inv sc1
	s_waitcnt vmcnt(0)

; #define LAS __attribute__((address_space(3)))
; __device__ __forceinline__ unsigned xb_ld(unsigned* p)              { asm volatile("" : "+v"(p)); return __hip_atomic_load(p, __ATOMIC_RELAXED, __HIP_MEMORY_SCOPE_AGENT); }
; __device__ __forceinline__ void xcd_barrier_complete(unsigned* bar, unsigned x, unsigned& nloc, unsigned& nx) {
;     const unsigned G = gridDim.x * gridDim.y * gridDim.z;
;     unsigned sum, cnt, mine, sp = 0u;
;     for (;;) {
;         sum = 0u; cnt = 0u; mine = 0u;
; #pragma unroll
;         for (unsigned j = 0; j < 16; ++j) { const unsigned c = xb_ld(&bar[XB_XCNT(j)]); sum += c; cnt += (c > 0u) ? 1u : 0u; mine = (j == x) ? c : mine; }
; __global__ void __launch_bounds__(NWAVES * 64, 2) mega_fwd(Args args) {
;     ...
;     unsigned char* ws = args.ws;
;     unsigned* ctl = (unsigned*)(ws + WS_CTL);
;     for (int u = threadIdx.x; u < (LDS_BYTES - LDSCTL_OFF) / 4; u += NWAVES * 64) ((LAS unsigned*)(L + LDSCTL_OFF))[u] = 0u;
;     __syncthreads();
;     XcdBarrier bar = xcd_barrier_post(ctl + CW_BAR, MISC + 8, (int)threadIdx.x);
;     const float* PAR = (const float*)(ws + WS_PAR);
;     const float* dec_f = PAR + PAR_DECF; const float* dec_b = PAR + PAR_DECB; const float* gn_w = PAR + PAR_GNW;
;     const float* lq1 = PAR + PAR_LQ1; const float* lk1 = PAR + PAR_LK1; const float* lq2 = PAR + PAR_LQ2; const float* lk2 = PAR + PAR_LK2;
;     const float* subln_w = PAR + PAR_SUBLN; const float* ln1_g = PAR + PAR_LN1G; const float* ln1_b = PAR + PAR_LN1B; const float* ln2_g = PAR + PAR_LN2G; const float* ln2_b = PAR + PAR_LN2B;
;     bf16* Win_t = (bf16*)(ws + WS_WIN); bf16* Wout_t = (bf16*)(ws + WS_WOUT); bf16* Wgu_t = (bf16*)(ws + WS_WGU); bf16* Wd_t = (bf16*)(ws + WS_WD);
;     bf16* XB = (bf16*)(ws + WS_XB); bf16* PROJ = (bf16*)(ws + WS_PROJ); bf16* HB = (bf16*)(ws + WS_PROJ); float* OS = (float*)(ws + WS_OS); bf16* KVB = (bf16*)(ws + WS_OS); bf16* SB = (bf16*)(ws + WS_OS + 128 * MiB); bf16* MP = (bf16*)(ws + WS_OS);
;     f32x2* tabR = (f32x2*)(ws + WS_TABR); f32x2* tabD = (f32x2*)(ws + WS_TABD);
;     unsigned* XQ = (unsigned*)(ws + WS_XQ); float* SAq = (float*)(ws + WS_SA);
.LBB0_140:
	s_add_u32 s64, s78, 0x100000
	s_addc_u32 s65, s79, 0
	s_add_u32 s66, s78, 0x100020
	s_addc_u32 s67, s79, 0
	s_add_u32 s0, s78, 0x100c40
	s_addc_u32 s1, s79, 0
	s_add_u32 s70, s78, 0x100840
	v_writelane_b32 v252, s0, 16
	s_addc_u32 s71, s79, 0
	s_movk_i32 s97, 0x181
	v_writelane_b32 v252, s1, 17
	s_add_u32 s0, s78, 0x102c40
	s_addc_u32 s1, s79, 0
	v_writelane_b32 v252, s0, 18
	v_mov_b32_e32 v251, 1
	v_mov_b32_e32 v193, 0
	v_writelane_b32 v252, s1, 19
	s_add_u32 s0, s78, 0x106c40
	s_addc_u32 s1, s79, 0
	v_writelane_b32 v252, s0, 20
	v_mov_b32_e32 v216, 0x260
	v_mov_b32_e32 v218, 0x7d7d7d7d
	v_writelane_b32 v252, s1, 21
	s_add_u32 s0, s78, 0x10ac40
	s_addc_u32 s1, s79, 0
	v_writelane_b32 v252, s0, 22
	v_mov_b32_e32 v219, 0x78787878
	s_mov_b32 s54, 0xffff0000
	v_writelane_b32 v252, s1, 23
	s_add_u32 s0, s78, 0x10ec40
	s_addc_u32 s1, s79, 0
	s_add_u32 s80, s78, 0x18e00000
	s_addc_u32 s81, s79, 0
	s_add_u32 s82, s78, 0x20e00000
	s_addc_u32 s83, s79, 0
	s_add_u32 s84, s78, 0x38e00000
	s_addc_u32 s85, s79, 0
	s_add_u32 s76, s78, 0x40e00000
	v_writelane_b32 v252, s0, 24
	s_addc_u32 s77, s79, 0
	s_movk_i32 s68, 0x6000
	v_writelane_b32 v252, s1, 25
	s_add_u32 s0, s78, 0x200000
	s_addc_u32 s1, s79, 0
	v_writelane_b32 v252, s0, 26
	s_mov_b32 s69, 0x3fffe
	s_mov_b32 s55, 0xf800000
	v_writelane_b32 v252, s1, 27
	s_add_u32 s0, s78, 0xa00000
	s_addc_u32 s1, s79, 0
	s_add_u32 s24, s78, 0xe400000
	s_addc_u32 s25, s79, 0
	v_writelane_b32 v252, s0, 28
	s_add_u32 s92, s78, 0x12400000
	s_addc_u32 s93, s79, 0
	v_writelane_b32 v252, s1, 29
	s_mul_i32 s1, s48, 0xfffffa00
	s_mul_hi_i32 s0, s48, 0xfffffa00
	s_add_u32 s4, s1, 0x800000
	s_addc_u32 s5, s0, 0
	v_writelane_b32 v252, s4, 30
	s_lshl_b64 s[0:1], s[48:49], 11
	s_mov_b32 s89, 0x40c0c00
	v_writelane_b32 v252, s5, 31
	v_writelane_b32 v252, s0, 32
	s_movk_i32 s86, 0x3100
	s_mov_b32 s87, 0xc3e00000
	v_writelane_b32 v252, s1, 33
	s_add_u32 s0, s33, 0x200
	s_addc_u32 s1, s40, 0
	s_add_u32 s28, s33, 0x400
	v_writelane_b32 v252, s0, 34
	s_addc_u32 s29, s40, 0
	s_mov_b64 s[14:15], 0x1000
	v_writelane_b32 v252, s1, 35
	s_add_u32 s0, s33, 0x500
	s_addc_u32 s1, s40, 0
	v_writelane_b32 v252, s0, 36
	s_mov_b32 s88, 0x3f9837f0
	s_nop 0
	v_writelane_b32 v252, s1, 37
	s_add_u32 s0, s33, 0x600
	s_addc_u32 s1, s40, 0
	v_writelane_b32 v252, s0, 38
	s_nop 1
	v_writelane_b32 v252, s1, 39
	s_add_u32 s0, s33, 0x700
	s_addc_u32 s1, s40, 0
	v_writelane_b32 v252, s0, 40
	s_nop 1
	v_writelane_b32 v252, s1, 41
	s_add_u32 s0, s33, 0x800
	s_addc_u32 s1, s40, 0
	v_writelane_b32 v252, s0, 42
	s_nop 1
	v_writelane_b32 v252, s1, 43
	s_add_u32 s0, s33, 0x900
	s_addc_u32 s1, s40, 0
	v_writelane_b32 v252, s0, 44
	s_nop 1
	v_writelane_b32 v252, s1, 45
	s_add_u32 s0, s33, 0xa00
	s_addc_u32 s1, s40, 0
	v_writelane_b32 v252, s0, 46
	s_nop 1
	v_writelane_b32 v252, s1, 47
	s_add_u32 s0, s33, 0xb00
	s_addc_u32 s1, s40, 0
	v_writelane_b32 v252, s0, 48
	s_nop 1
	v_writelane_b32 v252, s1, 49
	s_add_u32 s0, s33, 0xc00
	s_addc_u32 s1, s40, 0
	v_writelane_b32 v252, s0, 50
	s_nop 1
	v_writelane_b32 v252, s1, 51
	s_add_u32 s0, s33, 0xd00
	s_addc_u32 s1, s40, 0
	v_writelane_b32 v252, s0, 52
	s_nop 1
	v_writelane_b32 v252, s1, 53
	s_add_u32 s0, s33, 0xe00
	s_addc_u32 s1, s40, 0
	v_writelane_b32 v252, s0, 54
	s_nop 1
	v_writelane_b32 v252, s1, 55
	s_add_u32 s0, s33, 0xf00
	s_addc_u32 s1, s40, 0
	s_add_u32 s16, s33, 0x1000
	s_addc_u32 s17, s40, 0
	s_add_u32 s18, s33, 0x1100
	s_addc_u32 s19, s40, 0
	s_add_u32 s20, s33, 0x1200
	s_addc_u32 s21, s40, 0
	s_add_u32 s22, s33, 0x1300
	s_addc_u32 s23, s40, 0
	v_writelane_b32 v252, s0, 56
	s_cmp_eq_u32 s41, 15
	s_nop 0
	v_writelane_b32 v252, s1, 57
	s_cselect_b64 s[0:1], -1, 0
	v_writelane_b32 v252, s0, 58
	s_cmp_eq_u32 s41, 14
	s_nop 0
	v_writelane_b32 v252, s1, 59
	s_cselect_b64 s[0:1], -1, 0
	v_writelane_b32 v252, s0, 60
	s_cmp_eq_u32 s41, 13
	s_nop 0
	v_writelane_b32 v252, s1, 61
	s_cselect_b64 s[0:1], -1, 0
	v_writelane_b32 v252, s0, 62
	s_cmp_eq_u32 s41, 12
	s_nop 0
	v_writelane_b32 v252, s1, 63
	s_cselect_b64 s[0:1], -1, 0
	v_writelane_b32 v253, s0, 0
	s_cmp_eq_u32 s41, 11
	v_readlane_b32 s12, v252, 6
	v_writelane_b32 v253, s1, 1
	s_cselect_b64 s[0:1], -1, 0
	v_writelane_b32 v253, s0, 2
	s_cmp_eq_u32 s41, 10
	v_readlane_b32 s13, v252, 7
	v_writelane_b32 v253, s1, 3
	s_cselect_b64 s[0:1], -1, 0
	v_writelane_b32 v253, s0, 4
	s_cmp_eq_u32 s41, 9
	s_nop 0
	v_writelane_b32 v253, s1, 5
	s_cselect_b64 s[0:1], -1, 0
	v_writelane_b32 v253, s0, 6
	s_cmp_eq_u32 s41, 8
	s_nop 0
	v_writelane_b32 v253, s1, 7
	s_cselect_b64 s[0:1], -1, 0
	v_writelane_b32 v253, s0, 8
	s_cmp_eq_u32 s41, 7
	s_nop 0
	v_writelane_b32 v253, s1, 9
	s_cselect_b64 s[0:1], -1, 0
	v_writelane_b32 v253, s0, 10
	s_cmp_eq_u32 s41, 6
	s_nop 0
	v_writelane_b32 v253, s1, 11
	s_cselect_b64 s[0:1], -1, 0
	v_writelane_b32 v253, s0, 12
	s_cmp_eq_u32 s41, 5
	s_nop 0
	v_writelane_b32 v253, s1, 13
	s_cselect_b64 s[0:1], -1, 0
	v_writelane_b32 v253, s0, 14
	s_cmp_eq_u32 s41, 4
	s_nop 0
	v_writelane_b32 v253, s1, 15
	s_cselect_b64 s[0:1], -1, 0
	v_writelane_b32 v253, s0, 16
	s_cmp_eq_u32 s41, 3
	s_nop 0
	v_writelane_b32 v253, s1, 17
	s_cselect_b64 s[0:1], -1, 0
	v_writelane_b32 v253, s0, 18
	s_cmp_eq_u32 s41, 2
	s_nop 0
	v_writelane_b32 v253, s1, 19
	s_cselect_b64 s[0:1], -1, 0
	v_writelane_b32 v253, s0, 20
	s_cmp_eq_u32 s41, 1
	s_nop 0
	v_writelane_b32 v253, s1, 21
	s_cselect_b64 s[0:1], -1, 0
	v_writelane_b32 v253, s0, 22
	s_cmp_eq_u32 s41, 0
	s_nop 0
	v_writelane_b32 v253, s1, 23
	s_cselect_b64 s[0:1], -1, 0
	v_writelane_b32 v253, s0, 24
	s_nop 1
	v_writelane_b32 v253, s1, 25
	s_lshl_b32 s0, s41, 8
	s_add_u32 s0, s33, s0
	s_addc_u32 s1, s40, 0
; #define LAS __attribute__((address_space(3)))
;     __host__ __device__ bool next(int i, Unit& u) const {
;         const long L = (long)i * G + c; if (L >= nwg) return false;
;         int wgid = (int)L; { const int q = nwg / NXCD, r = nwg % NXCD, xcd = wgid % NXCD, off = wgid / NXCD; wgid = (xcd < r ? xcd * (q + 1) : r * (q + 1) + (xcd - r) * q) + off; }
;         const int nig = WGM * nN, gid = wgid / nig, fm = gid * WGM, gsz = (nM - fm) < WGM ? (nM - fm) : WGM;
;         u.pm = fm + ((wgid % nig) % gsz); u.pn = (wgid % nig) / gsz; return true;
; __global__ void __launch_bounds__(NWAVES * 64, 2) mega_fwd(Args args) {
;     ...
;     unsigned char* ws = args.ws;
;     unsigned* ctl = (unsigned*)(ws + WS_CTL);
;     for (int u = threadIdx.x; u < (LDS_BYTES - LDSCTL_OFF) / 4; u += NWAVES * 64) ((LAS unsigned*)(L + LDSCTL_OFF))[u] = 0u;
;     __syncthreads();
;     XcdBarrier bar = xcd_barrier_post(ctl + CW_BAR, MISC + 8, (int)threadIdx.x);
;     const float* PAR = (const float*)(ws + WS_PAR);
;     const float* dec_f = PAR + PAR_DECF; const float* dec_b = PAR + PAR_DECB; const float* gn_w = PAR + PAR_GNW;
;     const float* lq1 = PAR + PAR_LQ1; const float* lk1 = PAR + PAR_LK1; const float* lq2 = PAR + PAR_LQ2; const float* lk2 = PAR + PAR_LK2;
;     const float* subln_w = PAR + PAR_SUBLN; const float* ln1_g = PAR + PAR_LN1G; const float* ln1_b = PAR + PAR_LN1B; const float* ln2_g = PAR + PAR_LN2G; const float* ln2_b = PAR + PAR_LN2B;
;     bf16* Win_t = (bf16*)(ws + WS_WIN); bf16* Wout_t = (bf16*)(ws + WS_WOUT); bf16* Wgu_t = (bf16*)(ws + WS_WGU); bf16* Wd_t = (bf16*)(ws + WS_WD);
;     bf16* XB = (bf16*)(ws + WS_XB); bf16* PROJ = (bf16*)(ws + WS_PROJ); bf16* HB = (bf16*)(ws + WS_PROJ); float* OS = (float*)(ws + WS_OS); bf16* KVB = (bf16*)(ws + WS_OS); bf16* SB = (bf16*)(ws + WS_OS + 128 * MiB); bf16* MP = (bf16*)(ws + WS_OS);
;     f32x2* tabR = (f32x2*)(ws + WS_TABR); f32x2* tabD = (f32x2*)(ws + WS_TABD);
;     unsigned* XQ = (unsigned*)(ws + WS_XQ); float* SAq = (float*)(ws + WS_SA);
	s_add_u32 s4, s0, 0x1400
	s_addc_u32 s5, s1, 0
	s_add_u32 s26, s33, 0x3500
	s_addc_u32 s27, s40, 0
	v_writelane_b32 v253, s4, 26
	s_add_u32 s0, s33, 0x3400
	s_addc_u32 s1, s40, 0
	v_writelane_b32 v253, s5, 27
	v_writelane_b32 v253, s0, 28
	s_nop 1
	v_writelane_b32 v253, s1, 29
	s_add_u32 s0, s33, 0x3500
	s_addc_u32 s1, s40, 0
	v_writelane_b32 v253, s0, 30
	s_cmpk_lt_i32 s2, 0xc00
	s_movk_i32 s33, 0x7fff
	v_writelane_b32 v253, s1, 31
	s_cselect_b64 s[0:1], -1, 0
	v_writelane_b32 v253, s0, 32
	s_nop 1
	v_writelane_b32 v253, s1, 33
	s_lshr_b32 s0, s3, 29
	s_add_i32 s0, s2, s0
	s_ashr_i32 s8, s0, 3
	s_and_b32 s0, s0, -8
	s_sub_i32 s9, s2, s0
	s_cmpk_lt_i32 s2, 0x400
	s_cselect_b64 s[0:1], -1, 0
	v_writelane_b32 v253, s0, 34
	s_nop 1
	v_writelane_b32 v253, s1, 35
	s_add_u32 s0, s78, 0x112c40
	s_addc_u32 s1, s79, 0
	v_writelane_b32 v253, s0, 36
	s_cmpk_lt_i32 s2, 0x200
	s_nop 0
	v_writelane_b32 v253, s1, 37
	s_cselect_b64 s[0:1], -1, 0
	v_writelane_b32 v253, s0, 38
	s_cmpk_lg_i32 s48, 0x100
	s_nop 0
	v_writelane_b32 v253, s1, 39
	s_cselect_b64 s[0:1], -1, 0
	v_writelane_b32 v253, s0, 40
	s_nop 1
	v_writelane_b32 v253, s1, 41
	s_and_b32 s0, s2, 7
	s_lshl_b32 s0, s0, 1
	s_ashr_i32 s1, s2, 7
	s_add_i32 s0, s0, s1
	v_writelane_b32 v253, s0, 42
	s_lshl_b32 s0, s2, 5
	s_and_b32 s0, s0, 32
	s_ashr_i32 s1, s2, 3
	s_add_i32 s0, s0, s1
	v_writelane_b32 v253, s0, 43
	s_and_b32 s0, s1, 15
	v_writelane_b32 v253, s0, 44
	s_bfe_u32 s0, s2, 0x20001
	v_writelane_b32 v253, s0, 45
	s_lshl_b64 s[0:1], s[2:3], 18
	s_add_u32 s0, s84, s0
	v_writelane_b32 v253, s0, 46
	s_addc_u32 s0, s85, s1
	v_writelane_b32 v253, s0, 47
	s_lshl_b32 s0, s9, 7
	s_add_u32 s4, s78, 0x20000
	s_addc_u32 s5, s79, 0
	v_writelane_b32 v253, s4, 48
	s_cmpk_lt_i32 s2, 0x1580
	s_mul_i32 s1, s9, 0x81
	v_writelane_b32 v253, s5, 49
	s_cselect_b64 s[4:5], -1, 0
	v_writelane_b32 v253, s4, 50
	s_nop 1
	v_writelane_b32 v253, s5, 51
	s_add_u32 s4, s78, 0x2ac00
	s_addc_u32 s5, s79, 0
	s_cmp_lt_i32 s9, 0
	v_writelane_b32 v253, s4, 52
	s_cselect_b32 s0, s1, s0
	s_cselect_b32 s1, s97, 0x180
	v_writelane_b32 v253, s5, 53
	s_mul_i32 s1, s9, s1
	s_movk_i32 s4, 0x2b1
	s_cselect_b32 s10, s4, 0x2b0
	s_add_i32 s1, s1, s8
	s_mul_hi_i32 s4, s1, 0x2aaaaaab
	s_lshr_b32 s5, s4, 31
	s_ashr_i32 s4, s4, 6
	s_add_i32 s4, s4, s5
	s_mul_i32 s5, s4, 0x180
	s_sub_i32 s1, s1, s5
	s_bfe_u32 s5, s1, 0x3001c
	s_add_i32 s5, s1, s5
	s_and_b32 s6, s5, 0xfff8
	s_add_i32 s0, s0, s8
	s_sub_i32 s1, s1, s6
	s_ashr_i32 s6, s0, 31
	s_lshr_b32 s6, s6, 25
	s_add_i32 s6, s0, s6
	s_and_b32 s7, s6, 0xff80
	s_sub_i32 s0, s0, s7
	s_bfe_i32 s7, s0, 0x80000
	s_bfe_u32 s7, s7, 0x3000c
	s_add_i32 s7, s0, s7
	s_and_b32 s11, s7, 0xf8
	s_lshl_b32 s4, s4, 3
	s_sext_i32_i16 s1, s1
	s_sub_i32 s0, s0, s11
	s_add_i32 s30, s4, s1
	s_ashr_i32 s1, s6, 7
	s_bfe_i32 s4, s7, 0x80000
	s_lshl_b32 s1, s1, 3
	s_sext_i32_i16 s4, s4
	s_sext_i32_i8 s0, s0
	s_add_i32 s34, s1, s0
	s_lshr_b32 s0, s4, 3
	s_sext_i32_i16 s11, s5
	s_bfe_i64 s[0:1], s[0:1], 0x100000
	s_ashr_i32 s35, s34, 31
	s_ashr_i32 s31, s4, 3
	s_lshl_b64 s[4:5], s[0:1], 21
	s_ashr_i32 s0, s11, 3
	v_writelane_b32 v253, s0, 54
	s_lshr_b32 s0, s11, 3
	s_lshl_b64 s[6:7], s[34:35], 21
	s_add_u32 s4, s12, s4
	s_addc_u32 s5, s13, s5
	s_add_u32 s12, s4, 0x100000
	s_addc_u32 s13, s5, 0
	v_writelane_b32 v253, s12, 55
	s_add_u32 s6, s80, s6
	s_addc_u32 s7, s81, s7
	v_writelane_b32 v253, s13, 56
	s_add_u32 s12, s6, 0x100000
	v_writelane_b32 v253, s6, 57
	s_addc_u32 s13, s7, 0
	s_mul_i32 s1, s9, s10
	v_writelane_b32 v253, s7, 58
	v_writelane_b32 v253, s12, 59
	s_add_u32 s6, s4, 0x100080
	s_mov_b64 s[10:11], s[28:29]
	v_writelane_b32 v253, s13, 60
	v_writelane_b32 v253, s4, 61
	s_addc_u32 s7, s5, 0
	s_add_i32 s1, s1, s8
	v_writelane_b32 v253, s5, 62
	s_mul_hi_i32 s4, s1, 0x2fa0be83
	s_lshr_b32 s5, s4, 31
	s_ashr_i32 s4, s4, 7
	s_add_i32 s4, s4, s5
	s_mul_i32 s5, s4, 0x2b0
	s_sub_i32 s1, s1, s5
	s_bfe_u32 s5, s1, 0x3001c
	v_writelane_b32 v253, s6, 63
	s_add_i32 s5, s1, s5
	s_lshl_b32 s4, s4, 3
	v_writelane_b32 v254, s7, 0
	s_and_b32 s6, s5, 0xfff8
	s_sub_i32 s1, s1, s6
	s_sext_i32_i16 s5, s5
	s_sext_i32_i16 s1, s1
	s_add_i32 s8, s4, s1
	s_ashr_i32 s1, s5, 3
	v_writelane_b32 v254, s1, 1
	s_lshr_b32 s4, s5, 3
	s_mov_b32 s6, s8
	s_ashr_i32 s9, s8, 31
	s_bfe_i64 s[4:5], s[4:5], 0x100000
	v_writelane_b32 v254, s6, 2
	s_lshl_b64 s[4:5], s[4:5], 20
	s_mul_hi_i32 s1, s31, 0x310000
	v_writelane_b32 v254, s7, 3
	s_lshl_b64 s[6:7], s[8:9], 20
	v_readlane_b32 s8, v252, 14
	v_readlane_b32 s9, v252, 15
	s_add_u32 s4, s8, s4
	s_addc_u32 s5, s9, s5
	s_add_u32 s8, s4, 0x80000
	s_addc_u32 s9, s5, 0
	v_writelane_b32 v254, s8, 4
	s_add_u32 s6, s24, s6
	s_addc_u32 s7, s25, s7
	v_writelane_b32 v254, s9, 5
	v_writelane_b32 v254, s24, 6
	v_writelane_b32 v254, s25, 7
	s_add_u32 s8, s6, 0x80000
	v_writelane_b32 v254, s6, 8
	s_addc_u32 s9, s7, 0
	s_nop 0
	v_writelane_b32 v254, s7, 9
	v_writelane_b32 v254, s8, 10
	s_add_u32 s6, s4, 0x80080
	s_nop 0
; #define LAS __attribute__((address_space(3)))
; __device__ __forceinline__ unsigned xb_ld(unsigned* p)              { asm volatile("" : "+v"(p)); return __hip_atomic_load(p, __ATOMIC_RELAXED, __HIP_MEMORY_SCOPE_AGENT); }
; __device__ __forceinline__ unsigned xb_add(unsigned* p, unsigned v) { asm volatile("" : "+v"(p)); return __hip_atomic_fetch_add(p, v, __ATOMIC_RELAXED, __HIP_MEMORY_SCOPE_AGENT); }
; __device__ __forceinline__ void xcd_barrier(const XcdBarrier& b, int tid) {
;     ...
;             __builtin_amdgcn_fence(__ATOMIC_ACQUIRE, "agent");
;             xb_add(&bar[XB_XGEN(b.x)], 1u);
;             asm volatile("s_waitcnt vmcnt(0)" ::: "memory");
;         } else {
;             XB_SPIN(xb_ld(&bar[XB_XGEN(b.x)]) == gen, bar);
;             __builtin_amdgcn_fence(__ATOMIC_ACQUIRE, "agent");
;             asm volatile("s_waitcnt vmcnt(0)" ::: "memory");
; __global__ void __launch_bounds__(NWAVES * 64, 2) mega_fwd(Args args) {
;     ...
;     unsigned char* ws = args.ws;
;     unsigned* ctl = (unsigned*)(ws + WS_CTL);
;     for (int u = threadIdx.x; u < (LDS_BYTES - LDSCTL_OFF) / 4; u += NWAVES * 64) ((LAS unsigned*)(L + LDSCTL_OFF))[u] = 0u;
;     __syncthreads();
;     XcdBarrier bar = xcd_barrier_post(ctl + CW_BAR, MISC + 8, (int)threadIdx.x);
;     const float* PAR = (const float*)(ws + WS_PAR);
;     const float* dec_f = PAR + PAR_DECF; const float* dec_b = PAR + PAR_DECB; const float* gn_w = PAR + PAR_GNW;
;     const float* lq1 = PAR + PAR_LQ1; const float* lk1 = PAR + PAR_LK1; const float* lq2 = PAR + PAR_LQ2; const float* lk2 = PAR + PAR_LK2;
;     const float* subln_w = PAR + PAR_SUBLN; const float* ln1_g = PAR + PAR_LN1G; const float* ln1_b = PAR + PAR_LN1B; const float* ln2_g = PAR + PAR_LN2G; const float* ln2_b = PAR + PAR_LN2B;
;     bf16* Win_t = (bf16*)(ws + WS_WIN); bf16* Wout_t = (bf16*)(ws + WS_WOUT); bf16* Wgu_t = (bf16*)(ws + WS_WGU); bf16* Wd_t = (bf16*)(ws + WS_WD);
;     bf16* XB = (bf16*)(ws + WS_XB); bf16* PROJ = (bf16*)(ws + WS_PROJ); bf16* HB = (bf16*)(ws + WS_PROJ); float* OS = (float*)(ws + WS_OS); bf16* KVB = (bf16*)(ws + WS_OS); bf16* SB = (bf16*)(ws + WS_OS + 128 * MiB); bf16* MP = (bf16*)(ws + WS_OS);
;     f32x2* tabR = (f32x2*)(ws + WS_TABR); f32x2* tabD = (f32x2*)(ws + WS_TABD);
;     unsigned* XQ = (unsigned*)(ws + WS_XQ); float* SAq = (float*)(ws + WS_SA);
	v_writelane_b32 v254, s9, 11
	v_writelane_b32 v254, s4, 12
	s_addc_u32 s7, s5, 0
	s_nop 0
	v_writelane_b32 v254, s5, 13
	v_writelane_b32 v254, s6, 14
	s_mul_i32 s4, s31, 0x310000
	s_nop 0
	v_writelane_b32 v254, s7, 15
	v_readlane_b32 s6, v252, 8
	v_readlane_b32 s7, v252, 9
	s_add_u32 s6, s6, s4
	s_addc_u32 s7, s7, s1
	s_add_u32 s4, s6, 0x188000
	v_writelane_b32 v254, s31, 16
	s_addc_u32 s5, s7, 0
	v_writelane_b32 v254, s4, 17
	s_mul_hi_i32 s1, s34, 0x310000
	s_nop 0
	v_writelane_b32 v254, s5, 18
	s_mov_b32 s4, s34
	v_writelane_b32 v254, s4, 19
	s_nop 1
	v_writelane_b32 v254, s5, 20
	s_mul_i32 s4, s34, 0x310000
	s_add_u32 s4, s82, s4
	s_addc_u32 s5, s83, s1
	s_add_u32 s8, s4, 0x188000
	s_addc_u32 s9, s5, 0
	v_writelane_b32 v254, s8, 21
	s_mov_b64 s[34:35], 0x80
	s_nop 0
	v_writelane_b32 v254, s9, 22
	s_add_u32 s8, s6, 0x80
	s_addc_u32 s9, s7, 0
	v_writelane_b32 v254, s8, 23
	s_nop 1
	v_writelane_b32 v254, s9, 24
	s_add_u32 s8, s4, 0x80
	v_writelane_b32 v254, s4, 25
	s_addc_u32 s9, s5, 0
	s_nop 0
	v_writelane_b32 v254, s5, 26
	v_writelane_b32 v254, s8, 27
	s_add_u32 s4, s6, 0x188080
	s_nop 0
	v_writelane_b32 v254, s9, 28
	v_writelane_b32 v254, s6, 29
	s_addc_u32 s5, s7, 0
	s_ashr_i32 s31, s30, 31
	v_writelane_b32 v254, s7, 30
	v_writelane_b32 v254, s4, 31
	s_bfe_i64 s[0:1], s[0:1], 0x100000
	s_lshl_b64 s[0:1], s[0:1], 21
	v_writelane_b32 v254, s5, 32
	s_mov_b32 s4, s30
	v_writelane_b32 v254, s4, 33
	v_readlane_b32 s6, v252, 4
	v_readlane_b32 s7, v252, 5
	v_writelane_b32 v254, s5, 34
	s_lshl_b64 s[4:5], s[30:31], 21
	s_add_u32 s0, s6, s0
	s_addc_u32 s1, s7, s1
	s_add_u32 s6, s0, 0x100000
	s_addc_u32 s7, s1, 0
	v_writelane_b32 v254, s6, 35
	s_add_u32 s4, s80, s4
	s_addc_u32 s5, s81, s5
	v_writelane_b32 v254, s7, 36
	s_add_u32 s6, s4, 0x100000
	v_writelane_b32 v254, s4, 37
	s_addc_u32 s7, s5, 0
	s_mov_b32 s30, 0x41380000
	v_writelane_b32 v254, s5, 38
	v_writelane_b32 v254, s6, 39
	s_add_u32 s4, s0, 0x100080
	s_mov_b32 s31, 0x3f4ccccd
	v_writelane_b32 v254, s7, 40
	v_writelane_b32 v254, s0, 41
	s_addc_u32 s5, s1, 0
	s_lshl_b64 s[90:91], s[48:49], 15
	v_writelane_b32 v254, s1, 42
	v_writelane_b32 v254, s4, 43
	s_lshl_b64 s[0:1], s[2:3], 13
	s_lshl_b64 s[94:95], s[48:49], 16
	v_writelane_b32 v254, s5, 44
	v_writelane_b32 v254, s0, 45
	v_readlane_b32 s4, v252, 11
	v_readlane_b32 s5, v252, 12
	v_writelane_b32 v254, s1, 46
	s_lshl_b64 s[0:1], s[2:3], 14
	v_writelane_b32 v254, s0, 47
	s_nop 1
	v_writelane_b32 v254, s1, 48
	s_lshl_b64 s[0:1], s[48:49], 10
	s_add_u32 s0, s0, s4
	s_addc_u32 s1, s1, s5
	v_writelane_b32 v254, s0, 49
	s_nop 1
	v_writelane_b32 v254, s1, 50
	s_mul_i32 s1, s48, 0x600
	s_mul_hi_i32 s0, s48, 0x600
	s_add_u32 s6, s1, s4
	s_addc_u32 s7, s0, s5
	v_writelane_b32 v254, s6, 51
	s_add_u32 s0, s4, s58
	s_addc_u32 s1, s5, s59
	v_writelane_b32 v254, s7, 52
	v_writelane_b32 v254, s0, 53
	v_readlane_b32 s4, v252, 2
	v_readlane_b32 s5, v252, 3
	v_writelane_b32 v254, s1, 54
	s_lshl_b64 s[0:1], s[48:49], 14
	v_writelane_b32 v254, s0, 55
	s_load_dwordx2 s[6:7], s[4:5], 0x98
	s_nop 0
	v_writelane_b32 v254, s1, 56
	s_lshl_b64 s[0:1], s[48:49], 13
	v_writelane_b32 v254, s0, 57
	s_load_dwordx2 s[4:5], s[4:5], 0x8
	s_nop 0
	v_writelane_b32 v254, s1, 58
	s_add_u32 s0, s78, 0x21105000
	v_writelane_b32 v254, s0, 59
	s_addc_u32 s0, s79, 0
	v_writelane_b32 v254, s0, 60
	s_ashr_i32 s57, s56, 31
	v_writelane_b32 v254, s56, 61
	s_lshl_b64 s[0:1], s[56:57], 2
	s_lshl_b64 s[36:37], s[56:57], 14
	v_writelane_b32 v254, s57, 62
	v_writelane_b32 v254, s0, 63
	s_nop 1
	v_writelane_b32 v255, s1, 0
	s_lshl_b64 s[0:1], s[56:57], 12
	v_writelane_b32 v255, s0, 1
	s_nop 1
	v_writelane_b32 v255, s1, 2
	s_lshl_b64 s[0:1], s[56:57], 13
	v_writelane_b32 v255, s0, 3
	s_nop 1
	v_writelane_b32 v255, s1, 4
	s_add_u32 s0, s78, 0x38e01e00
	v_writelane_b32 v255, s0, 5
	s_addc_u32 s0, s79, 0
	v_writelane_b32 v255, s0, 6
	s_add_i32 s0, 0, 0x24960
	v_writelane_b32 v255, s0, 7
	s_add_i32 s0, 0, 0x24964
	v_writelane_b32 v255, s0, 8
	s_waitcnt lgkmcnt(0)
	v_writelane_b32 v255, s6, 9
	s_mov_b32 s1, 0
	s_nop 0
	v_writelane_b32 v255, s7, 10
	v_writelane_b32 v255, s4, 11
	s_mov_b64 s[6:7], -1
	s_nop 0
	v_writelane_b32 v255, s5, 12
	v_writelane_b32 v255, s58, 13
	s_mov_b64 s[4:5], 0
	s_nop 0
	v_writelane_b32 v255, s59, 14
	v_writelane_b32 v255, s76, 15
	s_nop 1
	v_writelane_b32 v255, s77, 16
	v_writelane_b32 v255, s10, 17
	s_nop 1
	v_writelane_b32 v255, s11, 18
	v_writelane_b32 v255, s90, 19
	s_nop 1
	v_writelane_b32 v255, s91, 20
	v_writelane_b32 v255, s94, 21
	s_nop 1
	v_writelane_b32 v255, s95, 22
	v_writelane_b32 v255, s78, 23
	s_nop 1
	v_writelane_b32 v255, s79, 24
	v_writelane_b32 v255, s96, 25
	v_writelane_b32 v255, s16, 26
	s_nop 1
	v_writelane_b32 v255, s17, 27
	v_writelane_b32 v255, s18, 28
	s_nop 1
	v_writelane_b32 v255, s19, 29
	s_branch .LBB0_143
.LBB0_141:
	s_or_b64 exec, exec, s[24:25]
	v_mov_b64_e32 v[0:1], s[26:27]
	s_waitcnt vmcnt(0) lgkmcnt(0)
	buffer_inv sc1
	s_waitcnt vmcnt(0)
